# v10 + rebalance W_D1 late conversions across idle GEMM tails: P20 86->66 tiles per WG; P1 +8, P8 +7, P11 +6 tiles per tail WG
# baseline (speedup 1.0000x reference)
.LBB0_100:
	s_cmpk_lt_i32 s76, 0xc0
	s_cselect_b64 s[2:3], -1, 0
	s_cmpk_lg_i32 s80, 0x100
	s_cselect_b64 s[8:9], -1, 0
	s_or_b64 s[2:3], s[2:3], s[8:9]
	s_and_b64 vcc, exec, s[2:3]
	s_cbranch_vccnz .LBB0_112
	s_mul_i32 s2, s76, 43
	s_add_i32 s3, s2, 0xffffdfc0
	s_addk_i32 s2, 0xdfeb
	s_min_i32 s2, s2, 0x6600
	s_cmp_ge_i32 s3, s2
	s_cbranch_scc1 .LBB0_112
	s_mov_b32 s99, s2
	s_mul_i32 s100, s76, 8
	s_add_i32 s100, s100, 0x8100
	s_add_i32 s2, s100, 8
	s_min_i32 s2, s2, 0x9100
	s_cmp_lt_i32 s100, s2
	s_cbranch_scc1 .Lrb_ok0
	s_mov_b32 s2, s99
	s_mov_b32 s99, -1
.Lrb_ok0:
	s_cmpk_gt_i32 s3, 0xfff
	s_cselect_b64 s[12:13], -1, 0
	s_and_b64 s[8:9], s[12:13], exec
	s_movk_i32 s14, 0x2dc
	s_cselect_b32 s18, s14, 0x2b4
	s_movk_i32 s14, 0x2e0
	s_cselect_b32 s8, 0xfffff000, 0
	s_movk_i32 s9, 0x2c0
	s_movk_i32 s10, 0x2d0
	s_movk_i32 s11, 0x2d8
	s_cselect_b32 s20, s14, 0x2b8
	s_movk_i32 s14, 0x2e4
	s_cselect_b32 s9, s9, 0x298
	s_cselect_b32 s10, s10, 0x2a8
	s_cselect_b32 s11, s11, 0x2b0
	s_cselect_b32 s21, s14, 0x2bc
	s_add_i32 s22, s8, s3
	s_add_u32 s16, s0, s9
	s_addc_u32 s17, s1, 0
	s_add_u32 s14, s0, s10
	s_addc_u32 s15, s1, 0
	s_add_u32 s10, s0, s11
	s_addc_u32 s11, s1, 0
	s_add_u32 s18, s0, s18
	s_addc_u32 s19, s1, 0
	s_add_u32 s8, s0, s20
	s_addc_u32 s9, s1, 0
	s_waitcnt vmcnt(0)
	s_barrier
	s_load_dword s20, s[8:9], 0x0
	s_add_u32 s8, s0, s21
	s_addc_u32 s9, s1, 0
	s_load_dword s21, s[8:9], 0x0
	s_waitcnt lgkmcnt(0)
	s_ashr_i32 s23, s20, 6
	s_abs_i32 s24, s23
	v_cvt_f32_u32_e32 v2, s24
	s_load_dwordx2 s[8:9], s[16:17], 0x0
	s_load_dword s20, s[18:19], 0x0
	s_sub_i32 s18, 0, s24
	s_abs_i32 s17, s22
	v_rcp_iflag_f32_e32 v2, v2
	s_xor_b32 s16, s22, s23
	s_ashr_i32 s16, s16, 31
	v_mul_f32_e32 v2, 0x4f7ffffe, v2
	v_cvt_u32_f32_e32 v2, v2
	s_nop 0
	v_readfirstlane_b32 s19, v2
	s_mul_i32 s18, s18, s19
	s_mul_hi_u32 s18, s19, s18
	s_add_i32 s19, s19, s18
	s_mul_hi_u32 s18, s17, s19
	s_mul_i32 s19, s18, s24
	s_sub_i32 s17, s17, s19
	s_add_i32 s19, s18, 1
	s_sub_i32 s25, s17, s24
	s_cmp_ge_u32 s17, s24
	s_cselect_b32 s18, s19, s18
	s_cselect_b32 s17, s25, s17
	s_add_i32 s19, s18, 1
	s_cmp_ge_u32 s17, s24
	s_cselect_b32 s17, s19, s18
	s_xor_b32 s17, s17, s16
	s_sub_i32 s17, s17, s16
	s_mul_i32 s16, s17, s23
	s_sub_i32 s18, s22, s16
	s_lshl_b32 s24, s18, 6
	s_cmp_lg_u32 s21, 1
	s_mov_b32 s16, s24
	s_cbranch_scc1 .LBB0_104
	s_lshl_b32 s16, s18, 5
	s_and_b32 s19, s18, 2
	s_and_b32 s16, s16, 0xffffff80
	s_and_b32 s18, s24, 64
	s_or_b32 s16, s16, s18
	s_movk_i32 s18, 0x2c8
	s_and_b64 s[12:13], s[12:13], exec
	s_cselect_b32 s12, s18, 0x2a0
	s_add_u32 s12, s0, s12
	s_addc_u32 s13, s1, 0
	s_load_dwordx2 s[12:13], s[12:13], 0x0
	s_cmp_eq_u32 s19, 0
	s_waitcnt lgkmcnt(0)
	s_cselect_b32 s9, s9, s13
	s_cselect_b32 s8, s8, s12

.LBB0_108:
	s_mov_b32 s8, s3
	s_add_i32 s3, s3, 1
	s_cmp_eq_u32 s3, s99
	s_cselect_b32 s3, s100, s3
	s_cmp_ge_i32 s3, s2
	s_cselect_b64 s[16:17], -1, 0
	s_cmp_lt_i32 s3, s2
	s_cselect_b32 s8, s3, s8
	s_cmpk_lt_u32 s8, 0x6600
	s_cselect_b32 s9, 12, 13
	s_add_i32 s10, s8, 0xfffff000
	s_cmpk_lt_u32 s10, 0x5600
	s_cselect_b32 s10, 0xfffff000, s25
	s_cmpk_gt_i32 s8, 0xfff
	s_cselect_b32 s9, s9, 11
	s_cselect_b32 s10, s10, 0
	s_add_i32 s22, s10, s8
	s_mul_i32 s9, s9, 40
	s_add_u32 s18, s0, s9
	s_addc_u32 s19, s1, 0
	s_load_dwordx4 s[8:11], s[18:19], 0xf8
	s_load_dwordx2 s[20:21], s[18:19], 0xe0
	s_abs_i32 s26, s22
	s_waitcnt lgkmcnt(0)
	s_ashr_i32 s23, s10, 6
	s_abs_i32 s10, s23
	v_cvt_f32_u32_e32 v251, s10
	s_sub_i32 s28, 0, s10
	s_xor_b32 s27, s22, s23
	s_ashr_i32 s27, s27, 31
	v_rcp_iflag_f32_e32 v251, v251
	s_nop 0
	v_mul_f32_e32 v251, 0x4f7ffffe, v251
	v_cvt_u32_f32_e32 v251, v251
	s_nop 0
	v_readfirstlane_b32 s29, v251
	s_mul_i32 s28, s28, s29
	s_mul_hi_u32 s28, s29, s28
	s_add_i32 s29, s29, s28
	s_mul_hi_u32 s28, s26, s29
	s_mul_i32 s29, s28, s10
	s_sub_i32 s26, s26, s29
	s_add_i32 s30, s28, 1
	s_sub_i32 s29, s26, s10
	s_cmp_ge_u32 s26, s10
	s_cselect_b32 s28, s30, s28
	s_cselect_b32 s26, s29, s26
	s_add_i32 s29, s28, 1
	s_cmp_ge_u32 s26, s10
	s_cselect_b32 s10, s29, s28
	s_xor_b32 s10, s10, s27
	s_sub_i32 s10, s10, s27
	s_mul_i32 s23, s10, s23
	s_sub_i32 s23, s22, s23
	s_lshl_b32 s26, s23, 6
	s_cmp_lg_u32 s11, 1
	s_mov_b32 s22, s26
	s_cbranch_scc1 .LBB0_110
	s_load_dwordx2 s[28:29], s[18:19], 0xe8
	s_lshl_b32 s22, s23, 5
	s_and_b32 s11, s23, 2
	s_and_b32 s22, s22, 0xffffff80
	s_and_b32 s23, s26, 64
	s_or_b32 s22, s22, s23
	s_cmp_eq_u32 s11, 0
	s_waitcnt lgkmcnt(0)
	s_cselect_b32 s21, s21, s29
	s_cselect_b32 s20, s20, s28

.LBB0_867:
	s_cmpk_lt_i32 s76, 0x80
	s_cselect_b64 s[2:3], -1, 0
	s_cmpk_lg_i32 s80, 0x100
	s_cselect_b64 s[6:7], -1, 0
	s_or_b64 s[2:3], s[2:3], s[6:7]
	s_and_b64 vcc, exec, s[2:3]
	s_cbranch_vccnz .LBB0_879
	s_mul_i32 s2, s76, 43
	s_add_i32 s3, s2, 0xfffff540
	s_addk_i32 s2, 0xf56b
	s_min_i32 s2, s2, 0x6600
	s_cmp_ge_i32 s3, s2
	s_cbranch_scc1 .LBB0_879
	s_mov_b32 s99, s2
	s_mul_i32 s100, s76, 7
	s_add_i32 s100, s100, 0x8580
	s_add_i32 s2, s100, 7
	s_min_i32 s2, s2, 0x9100
	s_cmp_lt_i32 s100, s2
	s_cbranch_scc1 .Lrb_ok1
	s_mov_b32 s2, s99
	s_mov_b32 s99, -1
.Lrb_ok1:
	s_cmpk_gt_i32 s3, 0xfff
	s_cselect_b64 s[6:7], -1, 0
	s_and_b64 s[8:9], s[6:7], exec
	s_movk_i32 s12, 0x2dc
	s_cselect_b32 s16, s12, 0x2b4
	s_movk_i32 s12, 0x2e0
	s_cselect_b32 s8, 0xfffff000, 0
	s_movk_i32 s9, 0x2c0
	s_movk_i32 s10, 0x2d0
	s_movk_i32 s11, 0x2d8
	s_cselect_b32 s18, s12, 0x2b8
	s_movk_i32 s12, 0x2e4
	s_cselect_b32 s9, s9, 0x298
	s_cselect_b32 s10, s10, 0x2a8
	s_cselect_b32 s11, s11, 0x2b0
	s_cselect_b32 s19, s12, 0x2bc
	s_add_i32 s20, s8, s3
	s_add_u32 s14, s0, s9
	s_addc_u32 s15, s1, 0
	s_add_u32 s12, s0, s10
	s_addc_u32 s13, s1, 0
	s_add_u32 s10, s0, s11
	s_addc_u32 s11, s1, 0
	s_add_u32 s16, s0, s16
	s_addc_u32 s17, s1, 0
	s_add_u32 s8, s0, s18
	s_addc_u32 s9, s1, 0
	s_waitcnt vmcnt(0)
	s_barrier
	s_load_dword s18, s[8:9], 0x0
	s_add_u32 s8, s0, s19
	s_addc_u32 s9, s1, 0
	s_load_dword s19, s[8:9], 0x0
	s_waitcnt lgkmcnt(0)
	s_ashr_i32 s21, s18, 6
	s_abs_i32 s22, s21
	v_cvt_f32_u32_e32 v2, s22
	s_load_dwordx2 s[8:9], s[14:15], 0x0
	s_load_dword s18, s[16:17], 0x0
	s_sub_i32 s16, 0, s22
	s_abs_i32 s15, s20
	v_rcp_iflag_f32_e32 v2, v2
	s_xor_b32 s14, s20, s21
	s_ashr_i32 s14, s14, 31
	v_mul_f32_e32 v2, 0x4f7ffffe, v2
	v_cvt_u32_f32_e32 v2, v2
	s_nop 0
	v_readfirstlane_b32 s17, v2
	s_mul_i32 s16, s16, s17
	s_mul_hi_u32 s16, s17, s16
	s_add_i32 s17, s17, s16
	s_mul_hi_u32 s16, s15, s17
	s_mul_i32 s17, s16, s22
	s_sub_i32 s15, s15, s17
	s_add_i32 s17, s16, 1
	s_sub_i32 s23, s15, s22
	s_cmp_ge_u32 s15, s22
	s_cselect_b32 s16, s17, s16
	s_cselect_b32 s15, s23, s15
	s_add_i32 s17, s16, 1
	s_cmp_ge_u32 s15, s22
	s_cselect_b32 s15, s17, s16
	s_xor_b32 s15, s15, s14
	s_sub_i32 s15, s15, s14
	s_mul_i32 s14, s15, s21
	s_sub_i32 s16, s20, s14
	s_lshl_b32 s22, s16, 6
	s_cmp_lg_u32 s19, 1
	s_mov_b32 s14, s22
	s_cbranch_scc1 .LBB0_871
	s_lshl_b32 s14, s16, 5
	s_and_b32 s17, s16, 2
	s_and_b32 s14, s14, 0xffffff80
	s_and_b32 s16, s22, 64
	s_or_b32 s14, s14, s16
	s_movk_i32 s16, 0x2c8
	s_and_b64 s[6:7], s[6:7], exec
	s_cselect_b32 s6, s16, 0x2a0
	s_add_u32 s6, s0, s6
	s_addc_u32 s7, s1, 0
	s_load_dwordx2 s[6:7], s[6:7], 0x0
	s_cmp_eq_u32 s17, 0
	s_waitcnt lgkmcnt(0)
	s_cselect_b32 s9, s9, s7
	s_cselect_b32 s8, s8, s6
.LBB0_871:
	s_load_dwordx2 s[6:7], s[12:13], 0x0
	v_and_b32_e32 v18, 60, v149
	v_add_u32_e32 v2, s14, v18
	s_waitcnt lgkmcnt(0)
	v_cmp_le_i32_e32 vcc, s18, v2
	v_mov_b32_e32 v2, 0
	s_and_saveexec_b64 s[12:13], vcc
	s_xor_b64 s[12:13], exec, s[12:13]
	s_or_saveexec_b64 s[16:17], s[12:13]
	s_load_dword s13, s[10:11], 0x0
	v_lshrrev_b32_e32 v19, 4, v0
	s_lshl_b32 s12, s15, 6
	v_mov_b32_e32 v3, 0
	v_mov_b32_e32 v4, 0
	v_mov_b32_e32 v5, 0
	v_mov_b32_e32 v6, 0
	v_mov_b32_e32 v7, 0
	v_mov_b32_e32 v8, 0
	v_mov_b32_e32 v9, 0
	s_xor_b64 exec, exec, s[16:17]
	s_cbranch_execz .LBB0_873
	v_or_b32_e32 v6, s12, v19
	v_mad_i64_i32 v[2:3], s[10:11], v6, s18, 0
	s_ashr_i32 s15, s14, 31
	v_lshl_add_u64 v[2:3], v[2:3], 2, s[8:9]
	s_lshl_b64 s[10:11], s[14:15], 2
	v_lshl_add_u64 v[2:3], v[2:3], 0, s[10:11]
	v_lshlrev_b32_e32 v4, 2, v18
	v_mov_b32_e32 v5, 0
	v_lshl_add_u64 v[10:11], v[2:3], 0, v[4:5]
	v_add_u32_e32 v2, 32, v6
	v_mad_i64_i32 v[2:3], s[14:15], v2, s18, 0
	v_lshl_add_u64 v[2:3], v[2:3], 2, s[8:9]
	v_lshl_add_u64 v[2:3], v[2:3], 0, s[10:11]
	v_lshl_add_u64 v[12:13], v[2:3], 0, v[4:5]
	global_load_dwordx4 v[2:5], v[10:11], off
	global_load_dwordx4 v[6:9], v[12:13], off

.LBB0_874:
	s_or_b64 exec, exec, s[10:11]
	s_load_dwordx2 s[10:11], s[16:17], 0xf0
	ds_write2_b32 v24, v2, v6 offset1:32
	ds_write2_b32 v24, v3, v7 offset0:65 offset1:97
	ds_write2_b32 v24, v4, v8 offset0:130 offset1:162
	ds_write2_b32 v24, v5, v9 offset0:195 offset1:227
	s_waitcnt lgkmcnt(0)
	s_barrier
	ds_read2_b32 v[2:3], v25 offset1:1
	ds_read2_b32 v[4:5], v25 offset0:2 offset1:3
	ds_read2_b32 v[6:7], v25 offset0:4 offset1:5
	ds_read2_b32 v[8:9], v25 offset0:6 offset1:7
	s_waitcnt lgkmcnt(3)
	v_cvt_pk_bf16_f32 v2, v2, v3
	s_waitcnt lgkmcnt(2)
	v_cvt_pk_bf16_f32 v3, v4, v5
	s_waitcnt lgkmcnt(1)
	v_cvt_pk_bf16_f32 v4, v6, v7
	v_add_u32_e32 v6, s22, v148
	v_mad_i64_i32 v[6:7], s[16:17], v6, s13, 0
	v_lshl_add_u64 v[6:7], v[6:7], 1, s[6:7]
	s_ashr_i32 s13, s12, 31
	v_lshl_add_u64 v[6:7], s[12:13], 1, v[6:7]
	s_waitcnt lgkmcnt(0)
	v_cvt_pk_bf16_f32 v5, v8, v9
	v_lshl_add_u64 v[6:7], v[6:7], 0, v[22:23]
	global_store_dwordx4 v[6:7], v[2:5], off
	s_andn2_b64 vcc, exec, s[14:15]
	s_mov_b32 s12, s25
	s_mov_b32 s22, s24
	s_mov_b32 s13, s8
	s_mov_b64 s[6:7], s[10:11]
	s_barrier
	s_cbranch_vccz .LBB0_879
.LBB0_875:
	s_mov_b32 s8, s3
	s_add_i32 s3, s3, 1
	s_cmp_eq_u32 s3, s99
	s_cselect_b32 s3, s100, s3
	s_cmp_ge_i32 s3, s2
	s_cselect_b64 s[14:15], -1, 0
	s_cmp_lt_i32 s3, s2
	s_cselect_b32 s8, s3, s8
	s_cmpk_lt_u32 s8, 0x6600
	s_cselect_b32 s9, 12, 13
	s_add_i32 s10, s8, 0xfffff000
	s_cmpk_lt_u32 s10, 0x5600
	s_cselect_b32 s10, 0xfffff000, s23
	s_cmpk_gt_i32 s8, 0xfff
	s_cselect_b32 s9, s9, 11
	s_cselect_b32 s10, s10, 0
	s_add_i32 s20, s10, s8
	s_mul_i32 s9, s9, 40
	s_add_u32 s16, s0, s9
	s_addc_u32 s17, s1, 0
	s_load_dwordx4 s[8:11], s[16:17], 0xf8
	s_load_dwordx2 s[18:19], s[16:17], 0xe0
	s_abs_i32 s24, s20
	s_waitcnt lgkmcnt(0)
	s_ashr_i32 s21, s10, 6
	s_abs_i32 s10, s21
	v_cvt_f32_u32_e32 v251, s10
	s_sub_i32 s26, 0, s10
	s_xor_b32 s25, s20, s21
	s_ashr_i32 s25, s25, 31
	v_rcp_iflag_f32_e32 v251, v251
	s_nop 0
	v_mul_f32_e32 v251, 0x4f7ffffe, v251
	v_cvt_u32_f32_e32 v251, v251
	s_nop 0
	v_readfirstlane_b32 s27, v251
	s_mul_i32 s26, s26, s27
	s_mul_hi_u32 s26, s27, s26
	s_add_i32 s27, s27, s26
	s_mul_hi_u32 s26, s24, s27
	s_mul_i32 s27, s26, s10
	s_sub_i32 s24, s24, s27
	s_add_i32 s28, s26, 1
	s_sub_i32 s27, s24, s10
	s_cmp_ge_u32 s24, s10
	s_cselect_b32 s26, s28, s26
	s_cselect_b32 s24, s27, s24
	s_add_i32 s27, s26, 1
	s_cmp_ge_u32 s24, s10
	s_cselect_b32 s10, s27, s26
	s_xor_b32 s10, s10, s25
	s_sub_i32 s10, s10, s25
	s_mul_i32 s21, s10, s21
	s_sub_i32 s21, s20, s21
	s_lshl_b32 s24, s21, 6
	s_cmp_lg_u32 s11, 1
	s_mov_b32 s20, s24
	s_cbranch_scc1 .LBB0_877
	s_load_dwordx2 s[26:27], s[16:17], 0xe8
	s_lshl_b32 s20, s21, 5
	s_and_b32 s11, s21, 2
	s_and_b32 s20, s20, 0xffffff80
	s_and_b32 s21, s24, 64
	s_or_b32 s20, s20, s21
	s_cmp_eq_u32 s11, 0
	s_waitcnt lgkmcnt(0)
	s_cselect_b32 s19, s19, s27
	s_cselect_b32 s18, s18, s26

.LBB0_1094:
	s_cmp_lt_i32 s76, 64
	s_cselect_b64 s[2:3], -1, 0
	s_cmpk_lg_i32 s80, 0x100
	s_cselect_b64 s[6:7], -1, 0
	s_or_b64 s[2:3], s[2:3], s[6:7]
	s_and_b64 vcc, exec, s[2:3]
	s_cbranch_vccnz .LBB0_1106
	s_mul_i32 s2, s76, 43
	s_add_i32 s3, s2, 0x1580
	s_addk_i32 s2, 0x15ab
	s_min_i32 s2, s2, 0x6600
	s_cmp_ge_i32 s3, s2
	s_cbranch_scc1 .LBB0_1106
	s_mov_b32 s99, s2
	s_mul_i32 s100, s76, 6
	s_add_i32 s100, s100, 0x8b00
	s_add_i32 s2, s100, 6
	s_min_i32 s2, s2, 0x9100
	s_cmp_lt_i32 s100, s2
	s_cbranch_scc1 .Lrb_ok2
	s_mov_b32 s2, s99
	s_mov_b32 s99, -1
.Lrb_ok2:
	s_cmpk_gt_i32 s3, 0xfff
	s_cselect_b64 s[6:7], -1, 0
	s_and_b64 s[8:9], s[6:7], exec
	s_movk_i32 s12, 0x2dc
	s_cselect_b32 s16, s12, 0x2b4
	s_movk_i32 s12, 0x2e0
	s_cselect_b32 s8, 0xfffff000, 0
	s_movk_i32 s9, 0x2c0
	s_movk_i32 s10, 0x2d0
	s_movk_i32 s11, 0x2d8
	s_cselect_b32 s18, s12, 0x2b8
	s_movk_i32 s12, 0x2e4
	s_cselect_b32 s9, s9, 0x298
	s_cselect_b32 s10, s10, 0x2a8
	s_cselect_b32 s11, s11, 0x2b0
	s_cselect_b32 s19, s12, 0x2bc
	s_add_i32 s20, s8, s3
	s_add_u32 s14, s0, s9
	s_addc_u32 s15, s1, 0
	s_add_u32 s12, s0, s10
	s_addc_u32 s13, s1, 0
	s_add_u32 s10, s0, s11
	s_addc_u32 s11, s1, 0
	s_add_u32 s16, s0, s16
	s_addc_u32 s17, s1, 0
	s_add_u32 s8, s0, s18
	s_addc_u32 s9, s1, 0
	s_waitcnt vmcnt(0)
	s_barrier
	s_load_dword s18, s[8:9], 0x0
	s_add_u32 s8, s0, s19
	s_addc_u32 s9, s1, 0
	s_load_dword s19, s[8:9], 0x0
	s_waitcnt lgkmcnt(0)
	s_ashr_i32 s21, s18, 6
	s_abs_i32 s22, s21
	v_cvt_f32_u32_e32 v2, s22
	s_load_dwordx2 s[8:9], s[14:15], 0x0
	s_load_dword s18, s[16:17], 0x0
	s_sub_i32 s16, 0, s22
	s_abs_i32 s15, s20
	v_rcp_iflag_f32_e32 v2, v2
	s_xor_b32 s14, s20, s21
	s_ashr_i32 s14, s14, 31
	v_mul_f32_e32 v2, 0x4f7ffffe, v2
	v_cvt_u32_f32_e32 v2, v2
	s_nop 0
	v_readfirstlane_b32 s17, v2
	s_mul_i32 s16, s16, s17
	s_mul_hi_u32 s16, s17, s16
	s_add_i32 s17, s17, s16
	s_mul_hi_u32 s16, s15, s17
	s_mul_i32 s17, s16, s22
	s_sub_i32 s15, s15, s17
	s_add_i32 s17, s16, 1
	s_sub_i32 s23, s15, s22
	s_cmp_ge_u32 s15, s22
	s_cselect_b32 s16, s17, s16
	s_cselect_b32 s15, s23, s15
	s_add_i32 s17, s16, 1
	s_cmp_ge_u32 s15, s22
	s_cselect_b32 s15, s17, s16
	s_xor_b32 s15, s15, s14
	s_sub_i32 s15, s15, s14
	s_mul_i32 s14, s15, s21
	s_sub_i32 s16, s20, s14
	s_lshl_b32 s22, s16, 6
	s_cmp_lg_u32 s19, 1
	s_mov_b32 s14, s22
	s_cbranch_scc1 .LBB0_1098
	s_lshl_b32 s14, s16, 5
	s_and_b32 s17, s16, 2
	s_and_b32 s14, s14, 0xffffff80
	s_and_b32 s16, s22, 64
	s_or_b32 s14, s14, s16
	s_movk_i32 s16, 0x2c8
	s_and_b64 s[6:7], s[6:7], exec
	s_cselect_b32 s6, s16, 0x2a0
	s_add_u32 s6, s0, s6
	s_addc_u32 s7, s1, 0
	s_load_dwordx2 s[6:7], s[6:7], 0x0
	s_cmp_eq_u32 s17, 0
	s_waitcnt lgkmcnt(0)
	s_cselect_b32 s9, s9, s7
	s_cselect_b32 s8, s8, s6
.LBB0_1098:
	s_load_dwordx2 s[6:7], s[12:13], 0x0
	v_and_b32_e32 v18, 60, v152
	v_add_u32_e32 v2, s14, v18
	s_waitcnt lgkmcnt(0)
	v_cmp_le_i32_e32 vcc, s18, v2
	v_mov_b32_e32 v2, 0
	s_and_saveexec_b64 s[12:13], vcc
	s_xor_b64 s[12:13], exec, s[12:13]
	s_or_saveexec_b64 s[16:17], s[12:13]
	s_load_dword s13, s[10:11], 0x0
	v_lshrrev_b32_e32 v19, 4, v0
	s_lshl_b32 s12, s15, 6
	v_mov_b32_e32 v3, 0
	v_mov_b32_e32 v4, 0
	v_mov_b32_e32 v5, 0
	v_mov_b32_e32 v6, 0
	v_mov_b32_e32 v7, 0
	v_mov_b32_e32 v8, 0
	v_mov_b32_e32 v9, 0
	s_xor_b64 exec, exec, s[16:17]
	s_cbranch_execz .LBB0_1100
	v_or_b32_e32 v6, s12, v19
	v_mad_i64_i32 v[2:3], s[10:11], v6, s18, 0
	s_ashr_i32 s15, s14, 31
	v_lshl_add_u64 v[2:3], v[2:3], 2, s[8:9]
	s_lshl_b64 s[10:11], s[14:15], 2
	v_lshl_add_u64 v[2:3], v[2:3], 0, s[10:11]
	v_lshlrev_b32_e32 v4, 2, v18
	v_mov_b32_e32 v5, 0
	v_lshl_add_u64 v[10:11], v[2:3], 0, v[4:5]
	v_add_u32_e32 v2, 32, v6
	v_mad_i64_i32 v[2:3], s[14:15], v2, s18, 0
	v_lshl_add_u64 v[2:3], v[2:3], 2, s[8:9]
	v_lshl_add_u64 v[2:3], v[2:3], 0, s[10:11]
	v_lshl_add_u64 v[12:13], v[2:3], 0, v[4:5]
	global_load_dwordx4 v[2:5], v[10:11], off
	global_load_dwordx4 v[6:9], v[12:13], off

.LBB0_1101:
	s_or_b64 exec, exec, s[10:11]
	s_load_dwordx2 s[10:11], s[16:17], 0xf0
	ds_write2_b32 v24, v2, v6 offset1:32
	ds_write2_b32 v24, v3, v7 offset0:65 offset1:97
	ds_write2_b32 v24, v4, v8 offset0:130 offset1:162
	ds_write2_b32 v24, v5, v9 offset0:195 offset1:227
	s_waitcnt lgkmcnt(0)
	s_barrier
	ds_read2_b32 v[2:3], v25 offset1:1
	ds_read2_b32 v[4:5], v25 offset0:2 offset1:3
	ds_read2_b32 v[6:7], v25 offset0:4 offset1:5
	ds_read2_b32 v[8:9], v25 offset0:6 offset1:7
	s_waitcnt lgkmcnt(3)
	v_cvt_pk_bf16_f32 v2, v2, v3
	s_waitcnt lgkmcnt(2)
	v_cvt_pk_bf16_f32 v3, v4, v5
	s_waitcnt lgkmcnt(1)
	v_cvt_pk_bf16_f32 v4, v6, v7
	v_add_u32_e32 v6, s22, v147
	v_mad_i64_i32 v[6:7], s[16:17], v6, s13, 0
	v_lshl_add_u64 v[6:7], v[6:7], 1, s[6:7]
	s_ashr_i32 s13, s12, 31
	v_lshl_add_u64 v[6:7], s[12:13], 1, v[6:7]
	s_waitcnt lgkmcnt(0)
	v_cvt_pk_bf16_f32 v5, v8, v9
	v_lshl_add_u64 v[6:7], v[6:7], 0, v[22:23]
	global_store_dwordx4 v[6:7], v[2:5], off
	s_andn2_b64 vcc, exec, s[14:15]
	s_mov_b32 s12, s25
	s_mov_b32 s22, s24
	s_mov_b32 s13, s8
	s_mov_b64 s[6:7], s[10:11]
	s_barrier
	s_cbranch_vccz .LBB0_1106
.LBB0_1102:
	s_mov_b32 s8, s3
	s_add_i32 s3, s3, 1
	s_cmp_eq_u32 s3, s99
	s_cselect_b32 s3, s100, s3
	s_cmp_ge_i32 s3, s2
	s_cselect_b64 s[14:15], -1, 0
	s_cmp_lt_i32 s3, s2
	s_cselect_b32 s8, s3, s8
	s_cmpk_lt_u32 s8, 0x6600
	s_cselect_b32 s9, 12, 13
	s_add_i32 s10, s8, 0xfffff000
	s_cmpk_lt_u32 s10, 0x5600
	s_cselect_b32 s10, 0xfffff000, s23
	s_cmpk_gt_i32 s8, 0xfff
	s_cselect_b32 s9, s9, 11
	s_cselect_b32 s10, s10, 0
	s_add_i32 s20, s10, s8
	s_mul_i32 s9, s9, 40
	s_add_u32 s16, s0, s9
	s_addc_u32 s17, s1, 0
	s_load_dwordx4 s[8:11], s[16:17], 0xf8
	s_load_dwordx2 s[18:19], s[16:17], 0xe0
	s_abs_i32 s24, s20
	s_waitcnt lgkmcnt(0)
	s_ashr_i32 s21, s10, 6
	s_abs_i32 s10, s21
	v_cvt_f32_u32_e32 v251, s10
	s_sub_i32 s26, 0, s10
	s_xor_b32 s25, s20, s21
	s_ashr_i32 s25, s25, 31
	v_rcp_iflag_f32_e32 v251, v251
	s_nop 0
	v_mul_f32_e32 v251, 0x4f7ffffe, v251
	v_cvt_u32_f32_e32 v251, v251
	s_nop 0
	v_readfirstlane_b32 s27, v251
	s_mul_i32 s26, s26, s27
	s_mul_hi_u32 s26, s27, s26
	s_add_i32 s27, s27, s26
	s_mul_hi_u32 s26, s24, s27
	s_mul_i32 s27, s26, s10
	s_sub_i32 s24, s24, s27
	s_add_i32 s28, s26, 1
	s_sub_i32 s27, s24, s10
	s_cmp_ge_u32 s24, s10
	s_cselect_b32 s26, s28, s26
	s_cselect_b32 s24, s27, s24
	s_add_i32 s27, s26, 1
	s_cmp_ge_u32 s24, s10
	s_cselect_b32 s10, s27, s26
	s_xor_b32 s10, s10, s25
	s_sub_i32 s10, s10, s25
	s_mul_i32 s21, s10, s21
	s_sub_i32 s21, s20, s21
	s_lshl_b32 s24, s21, 6
	s_cmp_lg_u32 s11, 1
	s_mov_b32 s20, s24
	s_cbranch_scc1 .LBB0_1104
	s_load_dwordx2 s[26:27], s[16:17], 0xe8
	s_lshl_b32 s20, s21, 5
	s_and_b32 s11, s21, 2
	s_and_b32 s20, s20, 0xffffff80
	s_and_b32 s21, s24, 64
	s_or_b32 s20, s20, s21
	s_cmp_eq_u32 s11, 0
	s_waitcnt lgkmcnt(0)
	s_cselect_b32 s19, s19, s27
	s_cselect_b32 s18, s18, s26

.LBB0_2281:
	s_cmpk_lt_i32 s76, 0x80
	s_cselect_b64 s[2:3], -1, 0
	s_cmpk_lg_i32 s80, 0x100
	s_cselect_b64 s[6:7], -1, 0
	s_or_b64 s[2:3], s[2:3], s[6:7]
	s_and_b64 vcc, exec, s[2:3]
	s_cbranch_vccnz .LBB0_2293
	s_mul_i32 s6, s76, 66
	s_add_i32 s3, s6, 0x4500
	s_add_i32 s2, s6, 0x4542
	s_cmp_ge_i32 s3, s2
	s_cbranch_scc1 .LBB0_2293
	s_load_dwordx4 s[8:11], s[0:1], 0x300
	s_load_dwordx2 s[12:13], s[0:1], 0x2e8
	s_add_i32 s14, s6, 0xffffdf00
	s_sub_i32 s6, 0x2100, s6
	s_max_i32 s6, s14, s6
	s_waitcnt lgkmcnt(0)
	s_ashr_i32 s7, s10, 6
	s_abs_i32 s10, s7
	v_cvt_f32_u32_e32 v2, s10
	s_sub_i32 s16, 0, s10
	s_xor_b32 s15, s14, s7
	s_ashr_i32 s15, s15, 31
	v_rcp_iflag_f32_e32 v2, v2
	s_waitcnt vmcnt(0)
	s_barrier
	v_mul_f32_e32 v2, 0x4f7ffffe, v2
	v_cvt_u32_f32_e32 v2, v2
	s_nop 0
	v_readfirstlane_b32 s17, v2
	s_mul_i32 s16, s16, s17
	s_mul_hi_u32 s16, s17, s16
	s_add_i32 s17, s17, s16
	s_mul_hi_u32 s16, s6, s17
	s_mul_i32 s17, s16, s10
	s_sub_i32 s6, s6, s17
	s_add_i32 s18, s16, 1
	s_sub_i32 s17, s6, s10
	s_cmp_ge_u32 s6, s10
	s_cselect_b32 s16, s18, s16
	s_cselect_b32 s6, s17, s6
	s_add_i32 s17, s16, 1
	s_cmp_ge_u32 s6, s10
	s_cselect_b32 s6, s17, s16
	s_xor_b32 s6, s6, s15
	s_sub_i32 s17, s6, s15
	s_mul_i32 s6, s17, s7
	s_sub_i32 s6, s14, s6
	s_lshl_b32 s24, s6, 6
	s_cmp_lg_u32 s11, 1
	s_mov_b32 s16, s24
	s_cbranch_scc1 .LBB0_2285
	s_and_b32 s10, s6, 2
	s_lshl_b32 s11, s6, 5
	s_load_dwordx2 s[6:7], s[0:1], 0x2f0
	s_and_b32 s11, s11, 0x7fffff80
	s_and_b32 s14, s24, 64
	s_or_b32 s16, s11, s14
	s_cmp_eq_u32 s10, 0
	s_waitcnt lgkmcnt(0)
	s_cselect_b32 s13, s13, s7
	s_cselect_b32 s12, s12, s6
